# v1: software-pipelined LDS fragment reads + SGPR-base LDS-DMA addressing in G1,G5,G6,G7 k-loops
# speedup vs baseline: 1.0017x; 1.0017x over previous
.LBB0_104:
	v_mov_b32_e32 v1, v168
	v_readlane_b32 s52, v254, 48
	v_readfirstlane_b32 s2, v1
	s_lshl_b32 s3, s2, 5
	s_lshl_b32 s2, s2, 6
	v_lshrrev_b32_e32 v3, 4, v1
	v_and_b32_e32 v4, 7, v1
	s_and_b32 s3, s3, 0xfffff000
	v_lshlrev_b32_e32 v1, 6, v1
	s_and_b32 s2, s2, 0x1000
	v_readlane_b32 s56, v254, 52
	v_bitop3_b32 v3, v3, v4, 3 bitop3:0x6c
	v_and_b32_e32 v1, 0x3c0, v1
	v_readlane_b32 s57, v254, 53
	s_add_u32 s36, s56, s21
	v_lshlrev_b32_e32 v69, 3, v3
	s_waitcnt vmcnt(0)
	v_or_b32_e32 v3, s3, v1
	v_or_b32_e32 v4, s2, v1
	s_addc_u32 s37, s57, s20
	s_lshl_b64 s[2:3], s[30:31], 1
	s_add_u32 s40, s56, s2
	s_waitcnt lgkmcnt(0)
	v_mov_b32_e32 v32, 0
	v_xor_b32_e32 v1, 32, v69
	s_addc_u32 s41, s57, s3
	s_mov_b64 s[42:43], 0
	s_mov_b32 s51, 0
	v_lshlrev_b32_e32 v3, 1, v3
	v_lshlrev_b32_e32 v68, 1, v4
	v_mov_b32_e32 v33, v32
	v_mov_b32_e32 v34, v32
	v_mov_b32_e32 v35, v32
	v_mov_b32_e32 v48, v32
	v_mov_b32_e32 v49, v32
	v_mov_b32_e32 v50, v32
	v_mov_b32_e32 v51, v32
	v_mov_b32_e32 v4, v32
	v_mov_b32_e32 v5, v32
	v_mov_b32_e32 v6, v32
	v_mov_b32_e32 v7, v32
	v_mov_b32_e32 v8, v32
	v_mov_b32_e32 v9, v32
	v_mov_b32_e32 v10, v32
	v_mov_b32_e32 v11, v32
	v_mov_b32_e32 v12, v32
	v_mov_b32_e32 v13, v32
	v_mov_b32_e32 v14, v32
	v_mov_b32_e32 v15, v32
	v_mov_b32_e32 v16, v32
	v_mov_b32_e32 v17, v32
	v_mov_b32_e32 v18, v32
	v_mov_b32_e32 v19, v32
	v_mov_b32_e32 v20, v32
	v_mov_b32_e32 v21, v32
	v_mov_b32_e32 v22, v32
	v_mov_b32_e32 v23, v32
	v_mov_b32_e32 v24, v32
	v_mov_b32_e32 v25, v32
	v_mov_b32_e32 v26, v32
	v_mov_b32_e32 v27, v32
	v_mov_b32_e32 v28, v32
	v_mov_b32_e32 v29, v32
	v_mov_b32_e32 v30, v32
	v_mov_b32_e32 v31, v32
	v_mov_b32_e32 v36, v32
	v_mov_b32_e32 v37, v32
	v_mov_b32_e32 v38, v32
	v_mov_b32_e32 v39, v32
	v_mov_b32_e32 v40, v32
	v_mov_b32_e32 v41, v32
	v_mov_b32_e32 v42, v32
	v_mov_b32_e32 v43, v32
	v_mov_b32_e32 v44, v32
	v_mov_b32_e32 v45, v32
	v_mov_b32_e32 v46, v32
	v_mov_b32_e32 v47, v32
	v_mov_b32_e32 v52, v32
	v_mov_b32_e32 v53, v32
	v_mov_b32_e32 v54, v32
	v_mov_b32_e32 v55, v32
	v_mov_b32_e32 v56, v32
	v_mov_b32_e32 v57, v32
	v_mov_b32_e32 v58, v32
	v_mov_b32_e32 v59, v32
	v_mov_b32_e32 v60, v32
	v_mov_b32_e32 v61, v32
	v_mov_b32_e32 v62, v32
	v_mov_b32_e32 v63, v32
	v_mov_b32_e32 v64, v32
	v_mov_b32_e32 v65, v32
	v_mov_b32_e32 v66, v32
	v_mov_b32_e32 v67, v32
	s_mov_b64 s[18:19], 0x1390080
	s_waitcnt vmcnt(0) lgkmcnt(0)
	s_barrier
	v_readlane_b32 s53, v254, 49
	v_readlane_b32 s54, v254, 50
	v_readlane_b32 s55, v254, 51
	v_readlane_b32 s58, v254, 54
	v_readlane_b32 s59, v254, 55
	v_lshlrev_b32_e32 v86, 1, v69
	v_add_u32_e32 v160, v3, v86
	v_add_u32_e32 v162, v68, v86
	v_lshlrev_b32_e32 v86, 1, v1
	v_add_u32_e32 v161, v3, v86
	v_add_u32_e32 v163, v68, v86
	v_lshrrev_b32_e32 v87, 3, v168
	v_xor_b32_e32 v86, v87, v168
	v_and_b32_e32 v86, 7, v86
	v_lshlrev_b32_e32 v86, 4, v86
	s_movk_i32 s35, 0x1600
	v_mad_u32_u24 v164, v87, s35, v86
	v_add_u32_e32 v165, 0x2c000, v164
	v_add_u32_e32 v166, 0x58000, v164
	v_add_u32_e32 v167, 0x84000, v164
	s_add_u32 s52, s36, 0x1390080
	s_addc_u32 s53, s37, 0
	s_add_u32 s54, s40, 0xf4b0080
	s_addc_u32 s55, s41, 0
	v_readfirstlane_b32 s35, v168
	s_lshl_b32 s35, s35, 4
	s_or_b32 s35, s35, 0x8000
.LBB0_105:
	ds_read_b128 v[70:73], v160
	ds_read_b128 v[74:77], v160 offset:2048
	ds_read_b128 v[78:81], v160 offset:4096
	ds_read_b128 v[82:85], v160 offset:6144
	ds_read_b128 v[112:115], v162 offset:16384
	ds_read_b128 v[116:119], v162 offset:18432
	ds_read_b128 v[120:123], v162 offset:20480
	ds_read_b128 v[124:127], v162 offset:22528
	s_mov_b32 m0, s35
	ds_read_b128 v[128:131], v161
	global_load_lds_dwordx4 v164, s[52:53]
	s_add_u32 m0, s35, 0x1000
	ds_read_b128 v[132:135], v161 offset:2048
	global_load_lds_dwordx4 v165, s[52:53]
	s_add_u32 m0, s35, 0x2000
	ds_read_b128 v[136:139], v161 offset:4096
	global_load_lds_dwordx4 v166, s[52:53]
	s_add_u32 m0, s35, 0x3000
	ds_read_b128 v[140:143], v161 offset:6144
	global_load_lds_dwordx4 v167, s[52:53]
	s_add_u32 m0, s35, 0x4000
	ds_read_b128 v[144:147], v163 offset:16384
	global_load_lds_dwordx4 v164, s[54:55]
	s_add_u32 m0, s35, 0x5000
	ds_read_b128 v[148:151], v163 offset:18432
	global_load_lds_dwordx4 v165, s[54:55]
	s_add_u32 m0, s35, 0x6000
	ds_read_b128 v[152:155], v163 offset:20480
	global_load_lds_dwordx4 v166, s[54:55]
	s_add_u32 m0, s35, 0x7000
	s_add_u32 s42, s42, 0x80
	global_load_lds_dwordx4 v167, s[54:55]
	s_add_u32 s52, s52, 0x80
	s_addc_u32 s53, s53, 0
	s_add_u32 s54, s54, 0x80
	s_addc_u32 s55, s55, 0
	s_xor_b32 s35, s35, 0x8000
	s_waitcnt lgkmcnt(10)
	v_mfma_f32_16x16x32_bf16 v[64:67], v[112:115], v[70:73], v[64:67]
	v_mfma_f32_16x16x32_bf16 v[60:63], v[112:115], v[74:77], v[60:63]
	v_mfma_f32_16x16x32_bf16 v[56:59], v[112:115], v[78:81], v[56:59]
	v_mfma_f32_16x16x32_bf16 v[52:55], v[112:115], v[82:85], v[52:55]
	ds_read_b128 v[156:159], v163 offset:22528
	s_waitcnt lgkmcnt(10)
	v_mfma_f32_16x16x32_bf16 v[44:47], v[116:119], v[70:73], v[44:47]
	v_mfma_f32_16x16x32_bf16 v[40:43], v[116:119], v[74:77], v[40:43]
	v_mfma_f32_16x16x32_bf16 v[36:39], v[116:119], v[78:81], v[36:39]
	v_mfma_f32_16x16x32_bf16 v[28:31], v[116:119], v[82:85], v[28:31]
	v_xor_b32_e32 v160, 0x8000, v160
	v_xor_b32_e32 v162, 0x8000, v162
	s_waitcnt lgkmcnt(9)
	v_mfma_f32_16x16x32_bf16 v[24:27], v[120:123], v[70:73], v[24:27]
	v_mfma_f32_16x16x32_bf16 v[20:23], v[120:123], v[74:77], v[20:23]
	v_mfma_f32_16x16x32_bf16 v[16:19], v[120:123], v[78:81], v[16:19]
	v_mfma_f32_16x16x32_bf16 v[12:15], v[120:123], v[82:85], v[12:15]
	v_xor_b32_e32 v161, 0x8000, v161
	v_xor_b32_e32 v163, 0x8000, v163
	s_waitcnt lgkmcnt(8)
	v_mfma_f32_16x16x32_bf16 v[8:11], v[124:127], v[70:73], v[8:11]
	v_mfma_f32_16x16x32_bf16 v[4:7], v[124:127], v[74:77], v[4:7]
	v_mfma_f32_16x16x32_bf16 v[48:51], v[124:127], v[78:81], v[48:51]
	v_mfma_f32_16x16x32_bf16 v[32:35], v[124:127], v[82:85], v[32:35]
	s_waitcnt lgkmcnt(3)
	v_mfma_f32_16x16x32_bf16 v[64:67], v[144:147], v[128:131], v[64:67]
	v_mfma_f32_16x16x32_bf16 v[60:63], v[144:147], v[132:135], v[60:63]
	v_mfma_f32_16x16x32_bf16 v[56:59], v[144:147], v[136:139], v[56:59]
	v_mfma_f32_16x16x32_bf16 v[52:55], v[144:147], v[140:143], v[52:55]
	s_waitcnt lgkmcnt(2)
	v_mfma_f32_16x16x32_bf16 v[44:47], v[148:151], v[128:131], v[44:47]
	v_mfma_f32_16x16x32_bf16 v[40:43], v[148:151], v[132:135], v[40:43]
	v_mfma_f32_16x16x32_bf16 v[36:39], v[148:151], v[136:139], v[36:39]
	v_mfma_f32_16x16x32_bf16 v[28:31], v[148:151], v[140:143], v[28:31]
	s_cmpk_eq_i32 s42, 0x1580
	s_waitcnt lgkmcnt(1)
	v_mfma_f32_16x16x32_bf16 v[24:27], v[152:155], v[128:131], v[24:27]
	v_mfma_f32_16x16x32_bf16 v[20:23], v[152:155], v[132:135], v[20:23]
	v_mfma_f32_16x16x32_bf16 v[16:19], v[152:155], v[136:139], v[16:19]
	v_mfma_f32_16x16x32_bf16 v[12:15], v[152:155], v[140:143], v[12:15]
	s_waitcnt lgkmcnt(0)
	s_waitcnt vmcnt(0)
	s_barrier
	v_mfma_f32_16x16x32_bf16 v[8:11], v[156:159], v[128:131], v[8:11]
	v_mfma_f32_16x16x32_bf16 v[4:7], v[156:159], v[132:135], v[4:7]
	v_mfma_f32_16x16x32_bf16 v[48:51], v[156:159], v[136:139], v[48:51]
	v_mfma_f32_16x16x32_bf16 v[32:35], v[156:159], v[140:143], v[32:35]
	s_cbranch_scc0 .LBB0_105
	s_mov_b32 s49, 0x8000
	v_lshl_add_u32 v69, v69, 1, s49
	v_add_u32_e32 v90, v69, v68
	ds_read_b128 v[70:73], v90 offset:16384
	v_add_u32_e32 v69, v69, v3
	ds_read_b128 v[74:77], v69
	ds_read_b128 v[78:81], v69 offset:2048
	ds_read_b128 v[82:85], v69 offset:4096
	ds_read_b128 v[86:89], v69 offset:6144
	v_lshl_add_u32 v1, v1, 1, s49
	v_add_u32_e32 v98, v1, v68
	ds_read_b128 v[94:97], v98 offset:20480
	s_waitcnt lgkmcnt(4)
	v_mfma_f32_16x16x32_bf16 v[64:67], v[70:73], v[74:77], v[64:67]
	v_add_u32_e32 v1, v1, v3
	s_add_i32 s44, s44, 1
	v_readlane_b32 s1, v254, 22
	s_waitcnt lgkmcnt(3)
	v_mfma_f32_16x16x32_bf16 v[60:63], v[70:73], v[78:81], v[60:63]
	s_mul_i32 s2, s44, s1
	v_readlane_b32 s1, v253, 34
	s_add_i32 s2, s2, s1
	s_waitcnt lgkmcnt(2)
	v_mfma_f32_16x16x32_bf16 v[56:59], v[70:73], v[82:85], v[56:59]
	s_cmpk_gt_u32 s2, 0x5f
	s_cselect_b64 s[36:37], -1, 0
	s_lshr_b32 s42, s2, 3
	s_waitcnt lgkmcnt(1)
	v_mfma_f32_16x16x32_bf16 v[52:55], v[70:73], v[86:89], v[52:55]
	ds_read_b128 v[70:73], v90 offset:18432
	v_readlane_b32 s1, v253, 62
	s_min_u32 s3, s2, 0x60
	s_waitcnt lgkmcnt(0)
	v_mfma_f32_16x16x32_bf16 v[44:47], v[70:73], v[74:77], v[44:47]
	s_add_i32 s42, s42, s1
	s_and_b32 s43, s3, 7
	s_cmpk_lt_u32 s2, 0x60
	v_mfma_f32_16x16x32_bf16 v[40:43], v[70:73], v[78:81], v[40:43]
	v_mfma_f32_16x16x32_bf16 v[36:39], v[70:73], v[82:85], v[36:39]
	v_mfma_f32_16x16x32_bf16 v[28:31], v[70:73], v[86:89], v[28:31]
	ds_read_b128 v[70:73], v90 offset:20480
	s_waitcnt lgkmcnt(0)
	v_mfma_f32_16x16x32_bf16 v[24:27], v[70:73], v[74:77], v[24:27]
	v_mfma_f32_16x16x32_bf16 v[20:23], v[70:73], v[78:81], v[20:23]
	v_mfma_f32_16x16x32_bf16 v[16:19], v[70:73], v[82:85], v[16:19]
	v_mfma_f32_16x16x32_bf16 v[12:15], v[70:73], v[86:89], v[12:15]
	ds_read_b128 v[70:73], v90 offset:22528
	ds_read_b128 v[90:93], v1 offset:6144
	s_waitcnt lgkmcnt(1)
	v_mfma_f32_16x16x32_bf16 v[8:11], v[70:73], v[74:77], v[8:11]
	v_mfma_f32_16x16x32_bf16 v[4:7], v[70:73], v[78:81], v[4:7]
	ds_read_b128 v[78:81], v1
	v_mfma_f32_16x16x32_bf16 v[74:77], v[70:73], v[82:85], v[48:51]
	ds_read_b128 v[82:85], v1 offset:2048
	s_nop 1
	ds_read_b128 v[48:51], v98 offset:16384
	v_mfma_f32_16x16x32_bf16 v[68:71], v[70:73], v[86:89], v[32:35]
	ds_read_b128 v[86:89], v1 offset:4096
	s_nop 1
	ds_read_b128 v[32:35], v98 offset:18432
	ds_read_b128 v[98:101], v98 offset:22528
	s_waitcnt lgkmcnt(3)
	v_mfma_f32_16x16x32_bf16 v[64:67], v[48:51], v[78:81], v[64:67]
	s_waitcnt vmcnt(0)
	s_waitcnt lgkmcnt(0)
	s_barrier
	v_mfma_f32_16x16x32_bf16 v[60:63], v[48:51], v[82:85], v[60:63]
	v_mfma_f32_16x16x32_bf16 v[56:59], v[48:51], v[86:89], v[56:59]
	v_mfma_f32_16x16x32_bf16 v[52:55], v[48:51], v[90:93], v[52:55]
	v_mfma_f32_16x16x32_bf16 v[48:51], v[32:35], v[78:81], v[44:47]
	v_mfma_f32_16x16x32_bf16 v[44:47], v[32:35], v[82:85], v[40:43]
	v_mfma_f32_16x16x32_bf16 v[40:43], v[32:35], v[86:89], v[36:39]
	v_mfma_f32_16x16x32_bf16 v[36:39], v[32:35], v[90:93], v[28:31]
	v_mfma_f32_16x16x32_bf16 v[32:35], v[94:97], v[78:81], v[24:27]
	v_mfma_f32_16x16x32_bf16 v[28:31], v[94:97], v[82:85], v[20:23]
	v_mfma_f32_16x16x32_bf16 v[24:27], v[94:97], v[86:89], v[16:19]
	v_mfma_f32_16x16x32_bf16 v[20:23], v[94:97], v[90:93], v[12:15]
	v_mfma_f32_16x16x32_bf16 v[16:19], v[98:101], v[78:81], v[8:11]
	v_mfma_f32_16x16x32_bf16 v[12:15], v[98:101], v[82:85], v[4:7]
	v_mfma_f32_16x16x32_bf16 v[8:11], v[98:101], v[86:89], v[74:77]
	v_mfma_f32_16x16x32_bf16 v[4:7], v[98:101], v[90:93], v[68:71]
	s_cbranch_scc0 .LBB0_99
	s_mul_i32 s30, s42, 0x58000
	s_lshl_b64 s[2:3], s[30:31], 1
	v_readlane_b32 s18, v252, 26
	v_readlane_b32 s19, v252, 27
	s_add_u32 s2, s18, s2
	s_addc_u32 s3, s19, s3
	s_mul_i32 s20, s43, 0xb0000
	v_readlane_b32 s1, v252, 28
	s_add_u32 s20, s1, s20
	v_readlane_b32 s1, v252, 29
	v_mov_b32_e32 v1, v168
	s_addc_u32 s21, s1, 0
	v_mov_b64_e32 v[68:69], s[2:3]
	v_ashrrev_i32_e32 v3, 3, v1
	v_xor_b32_e32 v70, v3, v1
	v_mov_b64_e32 v[72:73], s[20:21]
	v_mad_i64_i32 v[68:69], s[2:3], v3, s34, v[68:69]
	v_lshlrev_b32_e32 v70, 4, v70
	v_mad_i64_i32 v[72:73], s[2:3], v3, s34, v[72:73]
	v_lshlrev_b32_e32 v1, 4, v1
	v_and_b32_e32 v70, 0x70, v70
	v_mov_b32_e32 v71, v2
	v_readfirstlane_b32 s2, v1
	v_add_u32_e32 v3, 0x1000, v1
	v_lshl_add_u64 v[68:69], v[68:69], 0, v[70:71]
	s_mov_b32 m0, s2
	s_mov_b64 s[18:19], 0x2c000
	v_readfirstlane_b32 s2, v3
	v_add_u32_e32 v3, 0x2000, v1
	global_load_lds_dwordx4 v[68:69], off
	v_lshl_add_u64 v[74:75], v[68:69], 0, s[18:19]
	s_mov_b32 m0, s2
	s_mov_b64 s[20:21], 0x58000
	v_readfirstlane_b32 s2, v3
	v_add_u32_e32 v3, 0x3000, v1
	global_load_lds_dwordx4 v[74:75], off
	v_lshl_add_u64 v[74:75], v[68:69], 0, s[20:21]
	s_mov_b32 m0, s2
	s_mov_b64 s[34:35], 0x84000
	v_readfirstlane_b32 s2, v3
	v_add_u32_e32 v3, 0x4000, v1
	global_load_lds_dwordx4 v[74:75], off
	v_lshl_add_u64 v[68:69], v[68:69], 0, s[34:35]
	s_mov_b32 m0, s2
	v_readfirstlane_b32 s2, v3
	v_add_u32_e32 v3, 0x5000, v1
	global_load_lds_dwordx4 v[68:69], off
	v_lshl_add_u64 v[68:69], v[72:73], 0, v[70:71]
	s_mov_b32 m0, s2
	v_readfirstlane_b32 s2, v3
	v_add_u32_e32 v3, 0x6000, v1
	global_load_lds_dwordx4 v[68:69], off
	v_lshl_add_u64 v[70:71], v[68:69], 0, s[18:19]
	s_mov_b32 m0, s2
	v_readfirstlane_b32 s2, v3
	v_add_u32_e32 v1, 0x7000, v1
	global_load_lds_dwordx4 v[70:71], off
	v_lshl_add_u64 v[70:71], v[68:69], 0, s[20:21]
	s_mov_b32 m0, s2
	v_readfirstlane_b32 s2, v1
	global_load_lds_dwordx4 v[70:71], off
	v_lshl_add_u64 v[68:69], v[68:69], 0, s[34:35]
	s_mov_b32 m0, s2
	s_nop 0
	global_load_lds_dwordx4 v[68:69], off
	s_branch .LBB0_99

.LBB0_121:
	v_mov_b32_e32 v1, v168
	v_readlane_b32 s60, v254, 48
	v_readfirstlane_b32 s2, v1
	s_lshl_b32 s3, s2, 5
	s_lshl_b32 s2, s2, 6
	s_and_b32 s3, s3, 0xfffff000
	s_and_b32 s2, s2, 0x1000
	v_readlane_b32 s64, v254, 52
	v_lshrrev_b32_e32 v3, 4, v1
	v_and_b32_e32 v4, 7, v1
	v_lshlrev_b32_e32 v1, 6, v1
	v_readlane_b32 s65, v254, 53
	s_add_u32 s50, s64, s50
	v_bitop3_b32 v3, v3, v4, 3 bitop3:0x6c
	s_waitcnt vmcnt(0)
	v_and_b32_e32 v1, 0x3c0, v1
	s_addc_u32 s51, s65, s51
	v_lshlrev_b32_e32 v69, 3, v3
	v_or_b32_e32 v3, s3, v1
	v_or_b32_e32 v4, s2, v1
	s_add_u32 s52, s64, s52
	s_waitcnt lgkmcnt(0)
	v_mov_b32_e32 v32, 0
	v_xor_b32_e32 v1, 32, v69
	s_addc_u32 s53, s65, s53
	s_mov_b64 s[54:55], 0
	s_mov_b32 s45, 0
	v_lshlrev_b32_e32 v3, 1, v3
	v_lshlrev_b32_e32 v68, 1, v4
	v_mov_b32_e32 v33, v32
	v_mov_b32_e32 v34, v32
	v_mov_b32_e32 v35, v32
	v_mov_b32_e32 v48, v32
	v_mov_b32_e32 v49, v32
	v_mov_b32_e32 v50, v32
	v_mov_b32_e32 v51, v32
	v_mov_b32_e32 v4, v32
	v_mov_b32_e32 v5, v32
	v_mov_b32_e32 v6, v32
	v_mov_b32_e32 v7, v32
	v_mov_b32_e32 v8, v32
	v_mov_b32_e32 v9, v32
	v_mov_b32_e32 v10, v32
	v_mov_b32_e32 v11, v32
	v_mov_b32_e32 v12, v32
	v_mov_b32_e32 v13, v32
	v_mov_b32_e32 v14, v32
	v_mov_b32_e32 v15, v32
	v_mov_b32_e32 v16, v32
	v_mov_b32_e32 v17, v32
	v_mov_b32_e32 v18, v32
	v_mov_b32_e32 v19, v32
	v_mov_b32_e32 v20, v32
	v_mov_b32_e32 v21, v32
	v_mov_b32_e32 v22, v32
	v_mov_b32_e32 v23, v32
	v_mov_b32_e32 v24, v32
	v_mov_b32_e32 v25, v32
	v_mov_b32_e32 v26, v32
	v_mov_b32_e32 v27, v32
	v_mov_b32_e32 v28, v32
	v_mov_b32_e32 v29, v32
	v_mov_b32_e32 v30, v32
	v_mov_b32_e32 v31, v32
	v_mov_b32_e32 v36, v32
	v_mov_b32_e32 v37, v32
	v_mov_b32_e32 v38, v32
	v_mov_b32_e32 v39, v32
	v_mov_b32_e32 v40, v32
	v_mov_b32_e32 v41, v32
	v_mov_b32_e32 v42, v32
	v_mov_b32_e32 v43, v32
	v_mov_b32_e32 v44, v32
	v_mov_b32_e32 v45, v32
	v_mov_b32_e32 v46, v32
	v_mov_b32_e32 v47, v32
	v_mov_b32_e32 v52, v32
	v_mov_b32_e32 v53, v32
	v_mov_b32_e32 v54, v32
	v_mov_b32_e32 v55, v32
	v_mov_b32_e32 v56, v32
	v_mov_b32_e32 v57, v32
	v_mov_b32_e32 v58, v32
	v_mov_b32_e32 v59, v32
	v_mov_b32_e32 v60, v32
	v_mov_b32_e32 v61, v32
	v_mov_b32_e32 v62, v32
	v_mov_b32_e32 v63, v32
	v_mov_b32_e32 v64, v32
	v_mov_b32_e32 v65, v32
	v_mov_b32_e32 v66, v32
	v_mov_b32_e32 v67, v32
	s_waitcnt vmcnt(0) lgkmcnt(0)
	s_barrier
	v_readlane_b32 s61, v254, 49
	v_readlane_b32 s62, v254, 50
	v_readlane_b32 s63, v254, 51
	v_readlane_b32 s66, v254, 54
	v_readlane_b32 s67, v254, 55
	v_lshlrev_b32_e32 v86, 1, v69
	v_add_u32_e32 v160, v3, v86
	v_add_u32_e32 v162, v68, v86
	v_lshlrev_b32_e32 v86, 1, v1
	v_add_u32_e32 v161, v3, v86
	v_add_u32_e32 v163, v68, v86
	v_lshrrev_b32_e32 v87, 3, v168
	v_xor_b32_e32 v86, v87, v168
	v_and_b32_e32 v86, 7, v86
	v_lshlrev_b32_e32 v86, 4, v86
	s_movk_i32 s60, 0x800
	v_mad_u32_u24 v164, v87, s60, v86
	v_add_u32_e32 v165, 0x10000, v164
	v_add_u32_e32 v166, 0x20000, v164
	v_add_u32_e32 v167, 0x30000, v164
	s_add_u32 s58, s50, s68
	s_addc_u32 s59, s51, s69
	s_add_u32 s34, s52, 0xa130080
	s_addc_u32 s35, s53, 0
	v_readfirstlane_b32 s60, v168
	s_lshl_b32 s60, s60, 4
	s_or_b32 s60, s60, 0x8000
.LBB0_122:
	ds_read_b128 v[70:73], v160
	ds_read_b128 v[74:77], v160 offset:2048
	ds_read_b128 v[78:81], v160 offset:4096
	ds_read_b128 v[82:85], v160 offset:6144
	ds_read_b128 v[112:115], v162 offset:16384
	ds_read_b128 v[116:119], v162 offset:18432
	ds_read_b128 v[120:123], v162 offset:20480
	ds_read_b128 v[124:127], v162 offset:22528
	s_mov_b32 m0, s60
	ds_read_b128 v[128:131], v161
	global_load_lds_dwordx4 v164, s[58:59]
	s_add_u32 m0, s60, 0x1000
	ds_read_b128 v[132:135], v161 offset:2048
	global_load_lds_dwordx4 v165, s[58:59]
	s_add_u32 m0, s60, 0x2000
	ds_read_b128 v[136:139], v161 offset:4096
	global_load_lds_dwordx4 v166, s[58:59]
	s_add_u32 m0, s60, 0x3000
	ds_read_b128 v[140:143], v161 offset:6144
	global_load_lds_dwordx4 v167, s[58:59]
	s_add_u32 m0, s60, 0x4000
	ds_read_b128 v[144:147], v163 offset:16384
	global_load_lds_dwordx4 v164, s[34:35]
	s_add_u32 m0, s60, 0x5000
	ds_read_b128 v[148:151], v163 offset:18432
	global_load_lds_dwordx4 v165, s[34:35]
	s_add_u32 m0, s60, 0x6000
	ds_read_b128 v[152:155], v163 offset:20480
	global_load_lds_dwordx4 v166, s[34:35]
	s_add_u32 m0, s60, 0x7000
	s_add_u32 s54, s54, 0x80
	global_load_lds_dwordx4 v167, s[34:35]
	s_add_u32 s58, s58, 0x80
	s_addc_u32 s59, s59, 0
	s_add_u32 s34, s34, 0x80
	s_addc_u32 s35, s35, 0
	s_xor_b32 s60, s60, 0x8000
	s_waitcnt lgkmcnt(10)
	v_mfma_f32_16x16x32_bf16 v[64:67], v[112:115], v[70:73], v[64:67]
	v_mfma_f32_16x16x32_bf16 v[60:63], v[112:115], v[74:77], v[60:63]
	v_mfma_f32_16x16x32_bf16 v[56:59], v[112:115], v[78:81], v[56:59]
	v_mfma_f32_16x16x32_bf16 v[52:55], v[112:115], v[82:85], v[52:55]
	ds_read_b128 v[156:159], v163 offset:22528
	s_waitcnt lgkmcnt(10)
	v_mfma_f32_16x16x32_bf16 v[44:47], v[116:119], v[70:73], v[44:47]
	v_mfma_f32_16x16x32_bf16 v[40:43], v[116:119], v[74:77], v[40:43]
	v_mfma_f32_16x16x32_bf16 v[36:39], v[116:119], v[78:81], v[36:39]
	v_mfma_f32_16x16x32_bf16 v[28:31], v[116:119], v[82:85], v[28:31]
	v_xor_b32_e32 v160, 0x8000, v160
	v_xor_b32_e32 v162, 0x8000, v162
	s_waitcnt lgkmcnt(9)
	v_mfma_f32_16x16x32_bf16 v[24:27], v[120:123], v[70:73], v[24:27]
	v_mfma_f32_16x16x32_bf16 v[20:23], v[120:123], v[74:77], v[20:23]
	v_mfma_f32_16x16x32_bf16 v[16:19], v[120:123], v[78:81], v[16:19]
	v_mfma_f32_16x16x32_bf16 v[12:15], v[120:123], v[82:85], v[12:15]
	v_xor_b32_e32 v161, 0x8000, v161
	v_xor_b32_e32 v163, 0x8000, v163
	s_waitcnt lgkmcnt(8)
	v_mfma_f32_16x16x32_bf16 v[8:11], v[124:127], v[70:73], v[8:11]
	v_mfma_f32_16x16x32_bf16 v[4:7], v[124:127], v[74:77], v[4:7]
	v_mfma_f32_16x16x32_bf16 v[48:51], v[124:127], v[78:81], v[48:51]
	v_mfma_f32_16x16x32_bf16 v[32:35], v[124:127], v[82:85], v[32:35]
	s_waitcnt lgkmcnt(3)
	v_mfma_f32_16x16x32_bf16 v[64:67], v[144:147], v[128:131], v[64:67]
	v_mfma_f32_16x16x32_bf16 v[60:63], v[144:147], v[132:135], v[60:63]
	v_mfma_f32_16x16x32_bf16 v[56:59], v[144:147], v[136:139], v[56:59]
	v_mfma_f32_16x16x32_bf16 v[52:55], v[144:147], v[140:143], v[52:55]
	s_waitcnt lgkmcnt(2)
	v_mfma_f32_16x16x32_bf16 v[44:47], v[148:151], v[128:131], v[44:47]
	v_mfma_f32_16x16x32_bf16 v[40:43], v[148:151], v[132:135], v[40:43]
	v_mfma_f32_16x16x32_bf16 v[36:39], v[148:151], v[136:139], v[36:39]
	v_mfma_f32_16x16x32_bf16 v[28:31], v[148:151], v[140:143], v[28:31]
	s_cmpk_eq_i32 s54, 0x780
	s_waitcnt lgkmcnt(1)
	v_mfma_f32_16x16x32_bf16 v[24:27], v[152:155], v[128:131], v[24:27]
	v_mfma_f32_16x16x32_bf16 v[20:23], v[152:155], v[132:135], v[20:23]
	v_mfma_f32_16x16x32_bf16 v[16:19], v[152:155], v[136:139], v[16:19]
	v_mfma_f32_16x16x32_bf16 v[12:15], v[152:155], v[140:143], v[12:15]
	s_waitcnt lgkmcnt(0)
	s_waitcnt vmcnt(0)
	s_barrier
	v_mfma_f32_16x16x32_bf16 v[8:11], v[156:159], v[128:131], v[8:11]
	v_mfma_f32_16x16x32_bf16 v[4:7], v[156:159], v[132:135], v[4:7]
	v_mfma_f32_16x16x32_bf16 v[48:51], v[156:159], v[136:139], v[48:51]
	v_mfma_f32_16x16x32_bf16 v[32:35], v[156:159], v[140:143], v[32:35]
	s_cbranch_scc0 .LBB0_122
	s_mov_b32 s37, 0x8000
	v_lshl_add_u32 v69, v69, 1, s37
	v_add_u32_e32 v102, v69, v68
	ds_read_b128 v[70:73], v102 offset:16384
	v_add_u32_e32 v69, v69, v3
	ds_read_b128 v[74:77], v69
	ds_read_b128 v[78:81], v69 offset:2048
	v_lshl_add_u32 v1, v1, 1, s37
	v_add_u32_e32 v68, v1, v68
	v_add_u32_e32 v1, v1, v3
	s_and_b64 vcc, exec, s[48:49]
	s_waitcnt lgkmcnt(0)
	v_mfma_f32_16x16x32_bf16 v[82:85], v[70:73], v[78:81], v[60:63]
	ds_read_b128 v[86:89], v69 offset:6144
	ds_read_b128 v[106:109], v1 offset:6144
	s_nop 0
	ds_read_b128 v[60:63], v69 offset:4096
	v_mfma_f32_16x16x32_bf16 v[64:67], v[70:73], v[74:77], v[64:67]
	s_waitcnt lgkmcnt(0)
	v_mfma_f32_16x16x32_bf16 v[56:59], v[70:73], v[60:63], v[56:59]
	v_mfma_f32_16x16x32_bf16 v[70:73], v[70:73], v[86:89], v[52:55]
	s_nop 2
	ds_read_b128 v[52:55], v102 offset:18432
	s_waitcnt lgkmcnt(0)
	v_mfma_f32_16x16x32_bf16 v[94:97], v[52:55], v[60:63], v[36:39]
	s_nop 2
	ds_read_b128 v[36:39], v102 offset:20480
	s_waitcnt lgkmcnt(0)
	v_mfma_f32_16x16x32_bf16 v[98:101], v[36:39], v[86:89], v[12:15]
	s_nop 2
	ds_read_b128 v[12:15], v102 offset:22528
	ds_read_b128 v[102:105], v1 offset:2048
	v_mfma_f32_16x16x32_bf16 v[90:93], v[52:55], v[74:77], v[44:47]
	v_mfma_f32_16x16x32_bf16 v[24:27], v[36:39], v[74:77], v[24:27]
	s_waitcnt lgkmcnt(1)
	v_mfma_f32_16x16x32_bf16 v[8:11], v[12:15], v[74:77], v[8:11]
	v_mfma_f32_16x16x32_bf16 v[74:77], v[12:15], v[78:81], v[4:7]
	s_nop 2
	ds_read_b128 v[4:7], v68 offset:16384
	v_mfma_f32_16x16x32_bf16 v[28:31], v[52:55], v[86:89], v[28:31]
	v_mfma_f32_16x16x32_bf16 v[86:89], v[12:15], v[86:89], v[32:35]
	s_nop 2
	ds_read_b128 v[32:35], v1
	v_mfma_f32_16x16x32_bf16 v[40:43], v[52:55], v[78:81], v[40:43]
	s_waitcnt lgkmcnt(1)
	v_mfma_f32_16x16x32_bf16 v[52:55], v[4:7], v[102:105], v[82:85]
	s_nop 2
	ds_read_b128 v[82:85], v1 offset:4096
	v_mfma_f32_16x16x32_bf16 v[20:23], v[36:39], v[78:81], v[20:23]
	v_mfma_f32_16x16x32_bf16 v[16:19], v[36:39], v[60:63], v[16:19]
	v_mfma_f32_16x16x32_bf16 v[78:81], v[12:15], v[60:63], v[48:51]
	s_waitcnt lgkmcnt(1)
	v_mfma_f32_16x16x32_bf16 v[60:63], v[4:7], v[32:35], v[64:67]
	s_waitcnt lgkmcnt(0)
	v_mfma_f32_16x16x32_bf16 v[44:47], v[4:7], v[82:85], v[56:59]
	v_mfma_f32_16x16x32_bf16 v[36:39], v[4:7], v[106:109], v[70:73]
	ds_read_b128 v[4:7], v68 offset:18432
	s_waitcnt lgkmcnt(0)
	v_mfma_f32_16x16x32_bf16 v[64:67], v[4:7], v[32:35], v[90:93]
	v_mfma_f32_16x16x32_bf16 v[56:59], v[4:7], v[102:105], v[40:43]
	v_mfma_f32_16x16x32_bf16 v[48:51], v[4:7], v[82:85], v[94:97]
	v_mfma_f32_16x16x32_bf16 v[40:43], v[4:7], v[106:109], v[28:31]
	ds_read_b128 v[4:7], v68 offset:20480
	ds_read_b128 v[68:71], v68 offset:22528
	s_waitcnt vmcnt(0)
	s_waitcnt lgkmcnt(1)
	v_mfma_f32_16x16x32_bf16 v[28:31], v[4:7], v[32:35], v[24:27]
	s_waitcnt lgkmcnt(0)
	s_barrier
	v_mfma_f32_16x16x32_bf16 v[20:23], v[4:7], v[102:105], v[20:23]
	v_mfma_f32_16x16x32_bf16 v[12:15], v[4:7], v[82:85], v[16:19]
	v_mfma_f32_16x16x32_bf16 v[4:7], v[4:7], v[106:109], v[98:101]
	v_mfma_f32_16x16x32_bf16 v[32:35], v[68:71], v[32:35], v[8:11]
	v_mfma_f32_16x16x32_bf16 v[24:27], v[68:71], v[102:105], v[74:77]
	v_mfma_f32_16x16x32_bf16 v[16:19], v[68:71], v[82:85], v[78:81]
	v_mfma_f32_16x16x32_bf16 v[8:11], v[68:71], v[106:109], v[86:89]
	s_cbranch_vccz .LBB0_125
	s_ashr_i32 s45, s44, 31
	v_mov_b32_e32 v1, v168
	s_lshl_b64 s[2:3], s[44:45], 18
	v_readlane_b32 s18, v252, 32
	v_readlane_b32 s19, v252, 33
	v_ashrrev_i32_e32 v68, 3, v1
	s_add_u32 s2, s18, s2
	v_xor_b32_e32 v3, v68, v1
	v_ashrrev_i32_e32 v69, 31, v68
	s_addc_u32 s3, s19, s3
	v_lshlrev_b64 v[68:69], 11, v[68:69]
	v_lshlrev_b32_e32 v3, 4, v3
	v_lshlrev_b32_e32 v1, 4, v1
	s_ashr_i32 s37, s36, 31
	v_lshl_add_u64 v[70:71], s[2:3], 0, v[68:69]
	v_and_b32_e32 v72, 0x70, v3
	v_mov_b32_e32 v73, v2
	v_readfirstlane_b32 s2, v1
	v_add_u32_e32 v3, 0x1000, v1
	s_lshl_b64 s[20:21], s[36:37], 18
	v_readlane_b32 s1, v252, 34
	v_lshl_add_u64 v[70:71], v[70:71], 0, v[72:73]
	s_mov_b32 m0, s2
	v_readfirstlane_b32 s2, v3
	v_add_u32_e32 v3, 0x2000, v1
	s_add_u32 s20, s1, s20
	v_readlane_b32 s1, v252, 35
	global_load_lds_dwordx4 v[70:71], off
	v_lshl_add_u64 v[74:75], v[70:71], 0, s[24:25]
	s_mov_b32 m0, s2
	v_readfirstlane_b32 s2, v3
	v_add_u32_e32 v3, 0x3000, v1
	s_addc_u32 s21, s1, s21
	global_load_lds_dwordx4 v[74:75], off
	v_lshl_add_u64 v[74:75], v[70:71], 0, s[26:27]
	s_mov_b32 m0, s2
	v_readfirstlane_b32 s2, v3
	v_add_u32_e32 v3, 0x4000, v1
	v_lshl_add_u64 v[68:69], s[20:21], 0, v[68:69]
	global_load_lds_dwordx4 v[74:75], off
	v_lshl_add_u64 v[70:71], v[70:71], 0, s[28:29]
	s_mov_b32 m0, s2
	v_readfirstlane_b32 s2, v3
	v_add_u32_e32 v3, 0x5000, v1
	global_load_lds_dwordx4 v[70:71], off
	v_lshl_add_u64 v[68:69], v[68:69], 0, v[72:73]
	s_mov_b32 m0, s2
	v_readfirstlane_b32 s2, v3
	v_add_u32_e32 v3, 0x6000, v1
	global_load_lds_dwordx4 v[68:69], off
	v_lshl_add_u64 v[70:71], v[68:69], 0, s[24:25]
	s_mov_b32 m0, s2
	v_readfirstlane_b32 s2, v3
	v_add_u32_e32 v1, 0x7000, v1
	global_load_lds_dwordx4 v[70:71], off
	v_lshl_add_u64 v[70:71], v[68:69], 0, s[26:27]
	s_mov_b32 m0, s2
	v_readfirstlane_b32 s2, v1
	global_load_lds_dwordx4 v[70:71], off
	v_lshl_add_u64 v[68:69], v[68:69], 0, s[28:29]
	s_mov_b32 m0, s2
	s_nop 0
	global_load_lds_dwordx4 v[68:69], off

.LBB0_148:
	v_mov_b32_e32 v1, v168
	v_readlane_b32 s52, v254, 48
	v_readfirstlane_b32 s2, v1
	v_lshrrev_b32_e32 v3, 4, v1
	v_and_b32_e32 v4, 7, v1
	s_lshl_b32 s3, s2, 5
	v_lshlrev_b32_e32 v1, 6, v1
	s_lshl_b32 s2, s2, 6
	v_bitop3_b32 v3, v3, v4, 3 bitop3:0x6c
	s_and_b32 s3, s3, 0xfffff000
	v_and_b32_e32 v1, 0x3c0, v1
	s_and_b32 s2, s2, 0x1000
	v_lshlrev_b32_e32 v69, 3, v3
	v_or_b32_e32 v3, s3, v1
	v_or_b32_e32 v4, s2, v1
	s_lshl_b64 s[2:3], s[38:39], 11
	v_readlane_b32 s56, v254, 52
	v_readlane_b32 s57, v254, 53
	s_add_u32 s40, s56, s2
	s_waitcnt vmcnt(0)
	s_addc_u32 s41, s57, s3
	s_lshl_b64 s[2:3], s[30:31], 1
	s_add_u32 s42, s56, s2
	s_waitcnt lgkmcnt(0)
	v_mov_b32_e32 v32, 0
	v_xor_b32_e32 v1, 32, v69
	s_addc_u32 s43, s57, s3
	s_mov_b64 s[44:45], 0
	s_mov_b32 s51, 0
	v_lshlrev_b32_e32 v3, 1, v3
	v_lshlrev_b32_e32 v68, 1, v4
	v_mov_b32_e32 v33, v32
	v_mov_b32_e32 v34, v32
	v_mov_b32_e32 v35, v32
	v_mov_b32_e32 v48, v32
	v_mov_b32_e32 v49, v32
	v_mov_b32_e32 v50, v32
	v_mov_b32_e32 v51, v32
	v_mov_b32_e32 v4, v32
	v_mov_b32_e32 v5, v32
	v_mov_b32_e32 v6, v32
	v_mov_b32_e32 v7, v32
	v_mov_b32_e32 v8, v32
	v_mov_b32_e32 v9, v32
	v_mov_b32_e32 v10, v32
	v_mov_b32_e32 v11, v32
	v_mov_b32_e32 v12, v32
	v_mov_b32_e32 v13, v32
	v_mov_b32_e32 v14, v32
	v_mov_b32_e32 v15, v32
	v_mov_b32_e32 v16, v32
	v_mov_b32_e32 v17, v32
	v_mov_b32_e32 v18, v32
	v_mov_b32_e32 v19, v32
	v_mov_b32_e32 v20, v32
	v_mov_b32_e32 v21, v32
	v_mov_b32_e32 v22, v32
	v_mov_b32_e32 v23, v32
	v_mov_b32_e32 v24, v32
	v_mov_b32_e32 v25, v32
	v_mov_b32_e32 v26, v32
	v_mov_b32_e32 v27, v32
	v_mov_b32_e32 v28, v32
	v_mov_b32_e32 v29, v32
	v_mov_b32_e32 v30, v32
	v_mov_b32_e32 v31, v32
	v_mov_b32_e32 v36, v32
	v_mov_b32_e32 v37, v32
	v_mov_b32_e32 v38, v32
	v_mov_b32_e32 v39, v32
	v_mov_b32_e32 v40, v32
	v_mov_b32_e32 v41, v32
	v_mov_b32_e32 v42, v32
	v_mov_b32_e32 v43, v32
	v_mov_b32_e32 v44, v32
	v_mov_b32_e32 v45, v32
	v_mov_b32_e32 v46, v32
	v_mov_b32_e32 v47, v32
	v_mov_b32_e32 v52, v32
	v_mov_b32_e32 v53, v32
	v_mov_b32_e32 v54, v32
	v_mov_b32_e32 v55, v32
	v_mov_b32_e32 v56, v32
	v_mov_b32_e32 v57, v32
	v_mov_b32_e32 v58, v32
	v_mov_b32_e32 v59, v32
	v_mov_b32_e32 v60, v32
	v_mov_b32_e32 v61, v32
	v_mov_b32_e32 v62, v32
	v_mov_b32_e32 v63, v32
	v_mov_b32_e32 v64, v32
	v_mov_b32_e32 v65, v32
	v_mov_b32_e32 v66, v32
	v_mov_b32_e32 v67, v32
	s_mov_b64 s[18:19], 0x1390080
	s_waitcnt vmcnt(0) lgkmcnt(0)
	s_barrier
	v_readlane_b32 s53, v254, 49
	v_readlane_b32 s54, v254, 50
	v_readlane_b32 s55, v254, 51
	v_readlane_b32 s58, v254, 54
	v_readlane_b32 s59, v254, 55
	v_lshlrev_b32_e32 v86, 1, v69
	v_add_u32_e32 v160, v3, v86
	v_add_u32_e32 v162, v68, v86
	v_lshlrev_b32_e32 v86, 1, v1
	v_add_u32_e32 v161, v3, v86
	v_add_u32_e32 v163, v68, v86
	v_lshrrev_b32_e32 v87, 3, v168
	v_xor_b32_e32 v86, v87, v168
	v_and_b32_e32 v86, 7, v86
	v_lshlrev_b32_e32 v86, 4, v86
	s_movk_i32 s35, 0x800
	v_mad_u32_u24 v164, v87, s35, v86
	v_add_u32_e32 v165, 0x10000, v164
	v_add_u32_e32 v166, 0x20000, v164
	v_add_u32_e32 v167, 0x30000, v164
	s_add_u32 s52, s40, 0x1390080
	s_addc_u32 s53, s41, 0
	s_add_u32 s54, s42, 0x1190080
	s_addc_u32 s55, s43, 0
	v_readfirstlane_b32 s35, v168
	s_lshl_b32 s35, s35, 4
	s_or_b32 s35, s35, 0x8000
.LBB0_149:
	ds_read_b128 v[70:73], v160
	ds_read_b128 v[74:77], v160 offset:2048
	ds_read_b128 v[78:81], v160 offset:4096
	ds_read_b128 v[82:85], v160 offset:6144
	ds_read_b128 v[112:115], v162 offset:16384
	ds_read_b128 v[116:119], v162 offset:18432
	ds_read_b128 v[120:123], v162 offset:20480
	ds_read_b128 v[124:127], v162 offset:22528
	s_mov_b32 m0, s35
	ds_read_b128 v[128:131], v161
	global_load_lds_dwordx4 v164, s[52:53]
	s_add_u32 m0, s35, 0x1000
	ds_read_b128 v[132:135], v161 offset:2048
	global_load_lds_dwordx4 v165, s[52:53]
	s_add_u32 m0, s35, 0x2000
	ds_read_b128 v[136:139], v161 offset:4096
	global_load_lds_dwordx4 v166, s[52:53]
	s_add_u32 m0, s35, 0x3000
	ds_read_b128 v[140:143], v161 offset:6144
	global_load_lds_dwordx4 v167, s[52:53]
	s_add_u32 m0, s35, 0x4000
	ds_read_b128 v[144:147], v163 offset:16384
	global_load_lds_dwordx4 v164, s[54:55]
	s_add_u32 m0, s35, 0x5000
	ds_read_b128 v[148:151], v163 offset:18432
	global_load_lds_dwordx4 v165, s[54:55]
	s_add_u32 m0, s35, 0x6000
	ds_read_b128 v[152:155], v163 offset:20480
	global_load_lds_dwordx4 v166, s[54:55]
	s_add_u32 m0, s35, 0x7000
	s_add_u32 s44, s44, 0x80
	global_load_lds_dwordx4 v167, s[54:55]
	s_add_u32 s52, s52, 0x80
	s_addc_u32 s53, s53, 0
	s_add_u32 s54, s54, 0x80
	s_addc_u32 s55, s55, 0
	s_xor_b32 s35, s35, 0x8000
	s_waitcnt lgkmcnt(10)
	v_mfma_f32_16x16x32_bf16 v[64:67], v[112:115], v[70:73], v[64:67]
	v_mfma_f32_16x16x32_bf16 v[60:63], v[112:115], v[74:77], v[60:63]
	v_mfma_f32_16x16x32_bf16 v[56:59], v[112:115], v[78:81], v[56:59]
	v_mfma_f32_16x16x32_bf16 v[52:55], v[112:115], v[82:85], v[52:55]
	ds_read_b128 v[156:159], v163 offset:22528
	s_waitcnt lgkmcnt(10)
	v_mfma_f32_16x16x32_bf16 v[44:47], v[116:119], v[70:73], v[44:47]
	v_mfma_f32_16x16x32_bf16 v[40:43], v[116:119], v[74:77], v[40:43]
	v_mfma_f32_16x16x32_bf16 v[36:39], v[116:119], v[78:81], v[36:39]
	v_mfma_f32_16x16x32_bf16 v[28:31], v[116:119], v[82:85], v[28:31]
	v_xor_b32_e32 v160, 0x8000, v160
	v_xor_b32_e32 v162, 0x8000, v162
	s_waitcnt lgkmcnt(9)
	v_mfma_f32_16x16x32_bf16 v[24:27], v[120:123], v[70:73], v[24:27]
	v_mfma_f32_16x16x32_bf16 v[20:23], v[120:123], v[74:77], v[20:23]
	v_mfma_f32_16x16x32_bf16 v[16:19], v[120:123], v[78:81], v[16:19]
	v_mfma_f32_16x16x32_bf16 v[12:15], v[120:123], v[82:85], v[12:15]
	v_xor_b32_e32 v161, 0x8000, v161
	v_xor_b32_e32 v163, 0x8000, v163
	s_waitcnt lgkmcnt(8)
	v_mfma_f32_16x16x32_bf16 v[8:11], v[124:127], v[70:73], v[8:11]
	v_mfma_f32_16x16x32_bf16 v[4:7], v[124:127], v[74:77], v[4:7]
	v_mfma_f32_16x16x32_bf16 v[48:51], v[124:127], v[78:81], v[48:51]
	v_mfma_f32_16x16x32_bf16 v[32:35], v[124:127], v[82:85], v[32:35]
	s_waitcnt lgkmcnt(3)
	v_mfma_f32_16x16x32_bf16 v[64:67], v[144:147], v[128:131], v[64:67]
	v_mfma_f32_16x16x32_bf16 v[60:63], v[144:147], v[132:135], v[60:63]
	v_mfma_f32_16x16x32_bf16 v[56:59], v[144:147], v[136:139], v[56:59]
	v_mfma_f32_16x16x32_bf16 v[52:55], v[144:147], v[140:143], v[52:55]
	s_waitcnt lgkmcnt(2)
	v_mfma_f32_16x16x32_bf16 v[44:47], v[148:151], v[128:131], v[44:47]
	v_mfma_f32_16x16x32_bf16 v[40:43], v[148:151], v[132:135], v[40:43]
	v_mfma_f32_16x16x32_bf16 v[36:39], v[148:151], v[136:139], v[36:39]
	v_mfma_f32_16x16x32_bf16 v[28:31], v[148:151], v[140:143], v[28:31]
	s_cmpk_eq_i32 s44, 0x780
	s_waitcnt lgkmcnt(1)
	v_mfma_f32_16x16x32_bf16 v[24:27], v[152:155], v[128:131], v[24:27]
	v_mfma_f32_16x16x32_bf16 v[20:23], v[152:155], v[132:135], v[20:23]
	v_mfma_f32_16x16x32_bf16 v[16:19], v[152:155], v[136:139], v[16:19]
	v_mfma_f32_16x16x32_bf16 v[12:15], v[152:155], v[140:143], v[12:15]
	s_waitcnt lgkmcnt(0)
	s_waitcnt vmcnt(0)
	s_barrier
	v_mfma_f32_16x16x32_bf16 v[8:11], v[156:159], v[128:131], v[8:11]
	v_mfma_f32_16x16x32_bf16 v[4:7], v[156:159], v[132:135], v[4:7]
	v_mfma_f32_16x16x32_bf16 v[48:51], v[156:159], v[136:139], v[48:51]
	v_mfma_f32_16x16x32_bf16 v[32:35], v[156:159], v[140:143], v[32:35]
	s_cbranch_scc0 .LBB0_149
	s_mov_b32 s39, 0x8000
	v_lshl_add_u32 v69, v69, 1, s39
	v_add_u32_e32 v90, v69, v68
	ds_read_b128 v[70:73], v90 offset:16384
	v_add_u32_e32 v69, v69, v3
	ds_read_b128 v[74:77], v69
	ds_read_b128 v[78:81], v69 offset:2048
	ds_read_b128 v[82:85], v69 offset:4096
	ds_read_b128 v[86:89], v69 offset:6144
	v_lshl_add_u32 v1, v1, 1, s39
	v_add_u32_e32 v98, v1, v68
	ds_read_b128 v[94:97], v98 offset:20480
	s_waitcnt lgkmcnt(4)
	v_mfma_f32_16x16x32_bf16 v[64:67], v[70:73], v[74:77], v[64:67]
	v_add_u32_e32 v1, v1, v3
	s_add_i32 s46, s46, 1
	v_readlane_b32 s1, v254, 22
	s_waitcnt lgkmcnt(3)
	v_mfma_f32_16x16x32_bf16 v[60:63], v[70:73], v[78:81], v[60:63]
	s_mul_i32 s2, s46, s1
	v_readlane_b32 s1, v253, 34
	s_add_i32 s2, s2, s1
	s_waitcnt lgkmcnt(2)
	v_mfma_f32_16x16x32_bf16 v[56:59], v[70:73], v[82:85], v[56:59]
	s_cmpk_gt_u32 s2, 0x5f
	s_cselect_b64 s[40:41], -1, 0
	s_lshr_b32 s44, s2, 3
	s_waitcnt lgkmcnt(1)
	v_mfma_f32_16x16x32_bf16 v[52:55], v[70:73], v[86:89], v[52:55]
	ds_read_b128 v[70:73], v90 offset:18432
	v_readlane_b32 s1, v253, 62
	s_min_u32 s3, s2, 0x60
	s_waitcnt lgkmcnt(0)
	v_mfma_f32_16x16x32_bf16 v[44:47], v[70:73], v[74:77], v[44:47]
	s_add_i32 s44, s44, s1
	s_and_b32 s45, s3, 7
	s_cmpk_lt_u32 s2, 0x60
	v_mfma_f32_16x16x32_bf16 v[40:43], v[70:73], v[78:81], v[40:43]
	v_mfma_f32_16x16x32_bf16 v[36:39], v[70:73], v[82:85], v[36:39]
	v_mfma_f32_16x16x32_bf16 v[28:31], v[70:73], v[86:89], v[28:31]
	ds_read_b128 v[70:73], v90 offset:20480
	s_waitcnt lgkmcnt(0)
	v_mfma_f32_16x16x32_bf16 v[24:27], v[70:73], v[74:77], v[24:27]
	v_mfma_f32_16x16x32_bf16 v[20:23], v[70:73], v[78:81], v[20:23]
	v_mfma_f32_16x16x32_bf16 v[16:19], v[70:73], v[82:85], v[16:19]
	v_mfma_f32_16x16x32_bf16 v[12:15], v[70:73], v[86:89], v[12:15]
	ds_read_b128 v[70:73], v90 offset:22528
	ds_read_b128 v[90:93], v1 offset:6144
	s_waitcnt lgkmcnt(1)
	v_mfma_f32_16x16x32_bf16 v[8:11], v[70:73], v[74:77], v[8:11]
	v_mfma_f32_16x16x32_bf16 v[4:7], v[70:73], v[78:81], v[4:7]
	ds_read_b128 v[78:81], v1
	v_mfma_f32_16x16x32_bf16 v[74:77], v[70:73], v[82:85], v[48:51]
	ds_read_b128 v[82:85], v1 offset:2048
	s_nop 1
	ds_read_b128 v[48:51], v98 offset:16384
	v_mfma_f32_16x16x32_bf16 v[68:71], v[70:73], v[86:89], v[32:35]
	ds_read_b128 v[86:89], v1 offset:4096
	s_nop 1
	ds_read_b128 v[32:35], v98 offset:18432
	ds_read_b128 v[98:101], v98 offset:22528
	s_waitcnt lgkmcnt(3)
	v_mfma_f32_16x16x32_bf16 v[64:67], v[48:51], v[78:81], v[64:67]
	s_waitcnt vmcnt(0)
	s_waitcnt lgkmcnt(0)
	s_barrier
	v_mfma_f32_16x16x32_bf16 v[60:63], v[48:51], v[82:85], v[60:63]
	v_mfma_f32_16x16x32_bf16 v[56:59], v[48:51], v[86:89], v[56:59]
	v_mfma_f32_16x16x32_bf16 v[52:55], v[48:51], v[90:93], v[52:55]
	v_mfma_f32_16x16x32_bf16 v[48:51], v[32:35], v[78:81], v[44:47]
	v_mfma_f32_16x16x32_bf16 v[44:47], v[32:35], v[82:85], v[40:43]
	v_mfma_f32_16x16x32_bf16 v[40:43], v[32:35], v[86:89], v[36:39]
	v_mfma_f32_16x16x32_bf16 v[36:39], v[32:35], v[90:93], v[28:31]
	v_mfma_f32_16x16x32_bf16 v[32:35], v[94:97], v[78:81], v[24:27]
	v_mfma_f32_16x16x32_bf16 v[28:31], v[94:97], v[82:85], v[20:23]
	v_mfma_f32_16x16x32_bf16 v[24:27], v[94:97], v[86:89], v[16:19]
	v_mfma_f32_16x16x32_bf16 v[20:23], v[94:97], v[90:93], v[12:15]
	v_mfma_f32_16x16x32_bf16 v[16:19], v[98:101], v[78:81], v[8:11]
	v_mfma_f32_16x16x32_bf16 v[12:15], v[98:101], v[82:85], v[4:7]
	v_mfma_f32_16x16x32_bf16 v[8:11], v[98:101], v[86:89], v[74:77]
	v_mfma_f32_16x16x32_bf16 v[4:7], v[98:101], v[90:93], v[68:71]
	s_cbranch_scc0 .LBB0_143
	v_mov_b32_e32 v1, v168
	s_lshl_b32 s2, s44, 18
	v_readlane_b32 s18, v252, 26
	v_readlane_b32 s19, v252, 27
	v_ashrrev_i32_e32 v68, 3, v1
	s_add_u32 s2, s18, s2
	v_xor_b32_e32 v3, v68, v1
	v_ashrrev_i32_e32 v69, 31, v68
	s_addc_u32 s3, s19, 0
	v_lshlrev_b64 v[68:69], 11, v[68:69]
	v_lshlrev_b32_e32 v3, 4, v3
	v_lshlrev_b32_e32 v1, 4, v1
	v_lshl_add_u64 v[70:71], s[2:3], 0, v[68:69]
	v_and_b32_e32 v72, 0x70, v3
	v_mov_b32_e32 v73, v2
	v_readfirstlane_b32 s2, v1
	v_add_u32_e32 v3, 0x1000, v1
	s_lshl_b32 s20, s45, 18
	v_readlane_b32 s1, v252, 7
	v_lshl_add_u64 v[70:71], v[70:71], 0, v[72:73]
	s_mov_b32 m0, s2
	v_readfirstlane_b32 s2, v3
	v_add_u32_e32 v3, 0x2000, v1
	s_add_u32 s20, s1, s20
	v_readlane_b32 s1, v252, 8
	global_load_lds_dwordx4 v[70:71], off
	v_lshl_add_u64 v[74:75], v[70:71], 0, s[24:25]
	s_mov_b32 m0, s2
	v_readfirstlane_b32 s2, v3
	v_add_u32_e32 v3, 0x3000, v1
	s_addc_u32 s21, s1, 0
	global_load_lds_dwordx4 v[74:75], off
	v_lshl_add_u64 v[74:75], v[70:71], 0, s[26:27]
	s_mov_b32 m0, s2
	v_readfirstlane_b32 s2, v3
	v_add_u32_e32 v3, 0x4000, v1
	v_lshl_add_u64 v[68:69], s[20:21], 0, v[68:69]
	global_load_lds_dwordx4 v[74:75], off
	v_lshl_add_u64 v[70:71], v[70:71], 0, s[28:29]
	s_mov_b32 m0, s2
	v_readfirstlane_b32 s2, v3
	v_add_u32_e32 v3, 0x5000, v1
	global_load_lds_dwordx4 v[70:71], off
	v_lshl_add_u64 v[68:69], v[68:69], 0, v[72:73]
	s_mov_b32 m0, s2
	v_readfirstlane_b32 s2, v3
	v_add_u32_e32 v3, 0x6000, v1
	global_load_lds_dwordx4 v[68:69], off
	v_lshl_add_u64 v[70:71], v[68:69], 0, s[24:25]
	s_mov_b32 m0, s2
	v_readfirstlane_b32 s2, v3
	v_add_u32_e32 v1, 0x7000, v1
	global_load_lds_dwordx4 v[70:71], off
	v_lshl_add_u64 v[70:71], v[68:69], 0, s[26:27]
	s_mov_b32 m0, s2
	v_readfirstlane_b32 s2, v1
	global_load_lds_dwordx4 v[70:71], off
	v_lshl_add_u64 v[68:69], v[68:69], 0, s[28:29]
	s_mov_b32 m0, s2
	s_nop 0
	global_load_lds_dwordx4 v[68:69], off
	s_branch .LBB0_143

.LBB0_626:
	v_mov_b32_e32 v1, v168
	v_readlane_b32 s56, v254, 48
	v_readfirstlane_b32 s2, v1
	s_lshl_b32 s3, s2, 5
	s_lshl_b32 s2, s2, 6
	s_and_b32 s3, s3, 0xfffff000
	s_and_b32 s2, s2, 0x1000
	v_readlane_b32 s60, v254, 52
	v_lshrrev_b32_e32 v3, 4, v1
	v_and_b32_e32 v4, 7, v1
	v_lshlrev_b32_e32 v1, 6, v1
	v_readlane_b32 s61, v254, 53
	s_add_u32 s48, s60, s48
	v_bitop3_b32 v3, v3, v4, 3 bitop3:0x6c
	s_waitcnt vmcnt(0)
	v_and_b32_e32 v1, 0x3c0, v1
	s_addc_u32 s49, s61, s49
	v_lshlrev_b32_e32 v69, 3, v3
	v_or_b32_e32 v3, s3, v1
	v_or_b32_e32 v4, s2, v1
	s_add_u32 s50, s60, s50
	s_waitcnt lgkmcnt(0)
	v_mov_b32_e32 v32, 0
	v_xor_b32_e32 v1, 32, v69
	s_addc_u32 s51, s61, s51
	s_mov_b64 s[52:53], 0
	s_mov_b32 s41, 0
	v_lshlrev_b32_e32 v3, 1, v3
	v_lshlrev_b32_e32 v68, 1, v4
	v_mov_b32_e32 v33, v32
	v_mov_b32_e32 v34, v32
	v_mov_b32_e32 v35, v32
	v_mov_b32_e32 v48, v32
	v_mov_b32_e32 v49, v32
	v_mov_b32_e32 v50, v32
	v_mov_b32_e32 v51, v32
	v_mov_b32_e32 v4, v32
	v_mov_b32_e32 v5, v32
	v_mov_b32_e32 v6, v32
	v_mov_b32_e32 v7, v32
	v_mov_b32_e32 v8, v32
	v_mov_b32_e32 v9, v32
	v_mov_b32_e32 v10, v32
	v_mov_b32_e32 v11, v32
	v_mov_b32_e32 v12, v32
	v_mov_b32_e32 v13, v32
	v_mov_b32_e32 v14, v32
	v_mov_b32_e32 v15, v32
	v_mov_b32_e32 v16, v32
	v_mov_b32_e32 v17, v32
	v_mov_b32_e32 v18, v32
	v_mov_b32_e32 v19, v32
	v_mov_b32_e32 v20, v32
	v_mov_b32_e32 v21, v32
	v_mov_b32_e32 v22, v32
	v_mov_b32_e32 v23, v32
	v_mov_b32_e32 v24, v32
	v_mov_b32_e32 v25, v32
	v_mov_b32_e32 v26, v32
	v_mov_b32_e32 v27, v32
	v_mov_b32_e32 v28, v32
	v_mov_b32_e32 v29, v32
	v_mov_b32_e32 v30, v32
	v_mov_b32_e32 v31, v32
	v_mov_b32_e32 v36, v32
	v_mov_b32_e32 v37, v32
	v_mov_b32_e32 v38, v32
	v_mov_b32_e32 v39, v32
	v_mov_b32_e32 v40, v32
	v_mov_b32_e32 v41, v32
	v_mov_b32_e32 v42, v32
	v_mov_b32_e32 v43, v32
	v_mov_b32_e32 v44, v32
	v_mov_b32_e32 v45, v32
	v_mov_b32_e32 v46, v32
	v_mov_b32_e32 v47, v32
	v_mov_b32_e32 v52, v32
	v_mov_b32_e32 v53, v32
	v_mov_b32_e32 v54, v32
	v_mov_b32_e32 v55, v32
	v_mov_b32_e32 v56, v32
	v_mov_b32_e32 v57, v32
	v_mov_b32_e32 v58, v32
	v_mov_b32_e32 v59, v32
	v_mov_b32_e32 v60, v32
	v_mov_b32_e32 v61, v32
	v_mov_b32_e32 v62, v32
	v_mov_b32_e32 v63, v32
	v_mov_b32_e32 v64, v32
	v_mov_b32_e32 v65, v32
	v_mov_b32_e32 v66, v32
	v_mov_b32_e32 v67, v32
	s_waitcnt vmcnt(0)
	s_barrier
	v_readlane_b32 s57, v254, 49
	v_readlane_b32 s58, v254, 50
	v_readlane_b32 s59, v254, 51
	v_readlane_b32 s62, v254, 54
	v_readlane_b32 s63, v254, 55
	v_lshlrev_b32_e32 v86, 1, v69
	v_add_u32_e32 v160, v3, v86
	v_add_u32_e32 v162, v68, v86
	v_lshlrev_b32_e32 v86, 1, v1
	v_add_u32_e32 v161, v3, v86
	v_add_u32_e32 v163, v68, v86
	v_lshrrev_b32_e32 v87, 3, v168
	v_xor_b32_e32 v86, v87, v168
	v_and_b32_e32 v86, 7, v86
	v_lshlrev_b32_e32 v86, 4, v86
	s_movk_i32 s60, 0x800
	v_mad_u32_u24 v164, v87, s60, v86
	v_add_u32_e32 v165, 0x10000, v164
	v_add_u32_e32 v166, 0x20000, v164
	v_add_u32_e32 v167, 0x30000, v164
	s_add_u32 s56, s48, s68
	s_addc_u32 s57, s49, s69
	s_add_u32 s58, s50, 0x80080
	s_addc_u32 s59, s51, 0
	v_readfirstlane_b32 s60, v168
	s_lshl_b32 s60, s60, 4
	s_or_b32 s60, s60, 0x8000
.LBB0_627:
	ds_read_b128 v[70:73], v160
	ds_read_b128 v[74:77], v160 offset:2048
	ds_read_b128 v[78:81], v160 offset:4096
	ds_read_b128 v[82:85], v160 offset:6144
	ds_read_b128 v[112:115], v162 offset:16384
	ds_read_b128 v[116:119], v162 offset:18432
	ds_read_b128 v[120:123], v162 offset:20480
	ds_read_b128 v[124:127], v162 offset:22528
	s_mov_b32 m0, s60
	ds_read_b128 v[128:131], v161
	global_load_lds_dwordx4 v164, s[56:57]
	s_add_u32 m0, s60, 0x1000
	ds_read_b128 v[132:135], v161 offset:2048
	global_load_lds_dwordx4 v165, s[56:57]
	s_add_u32 m0, s60, 0x2000
	ds_read_b128 v[136:139], v161 offset:4096
	global_load_lds_dwordx4 v166, s[56:57]
	s_add_u32 m0, s60, 0x3000
	ds_read_b128 v[140:143], v161 offset:6144
	global_load_lds_dwordx4 v167, s[56:57]
	s_add_u32 m0, s60, 0x4000
	ds_read_b128 v[144:147], v163 offset:16384
	global_load_lds_dwordx4 v164, s[58:59]
	s_add_u32 m0, s60, 0x5000
	ds_read_b128 v[148:151], v163 offset:18432
	global_load_lds_dwordx4 v165, s[58:59]
	s_add_u32 m0, s60, 0x6000
	ds_read_b128 v[152:155], v163 offset:20480
	global_load_lds_dwordx4 v166, s[58:59]
	s_add_u32 m0, s60, 0x7000
	s_add_u32 s52, s52, 0x80
	global_load_lds_dwordx4 v167, s[58:59]
	s_add_u32 s56, s56, 0x80
	s_addc_u32 s57, s57, 0
	s_add_u32 s58, s58, 0x80
	s_addc_u32 s59, s59, 0
	s_xor_b32 s60, s60, 0x8000
	s_waitcnt lgkmcnt(10)
	v_mfma_f32_16x16x32_bf16 v[64:67], v[112:115], v[70:73], v[64:67]
	v_mfma_f32_16x16x32_bf16 v[60:63], v[112:115], v[74:77], v[60:63]
	v_mfma_f32_16x16x32_bf16 v[56:59], v[112:115], v[78:81], v[56:59]
	v_mfma_f32_16x16x32_bf16 v[52:55], v[112:115], v[82:85], v[52:55]
	ds_read_b128 v[156:159], v163 offset:22528
	s_waitcnt lgkmcnt(10)
	v_mfma_f32_16x16x32_bf16 v[44:47], v[116:119], v[70:73], v[44:47]
	v_mfma_f32_16x16x32_bf16 v[40:43], v[116:119], v[74:77], v[40:43]
	v_mfma_f32_16x16x32_bf16 v[36:39], v[116:119], v[78:81], v[36:39]
	v_mfma_f32_16x16x32_bf16 v[28:31], v[116:119], v[82:85], v[28:31]
	v_xor_b32_e32 v160, 0x8000, v160
	v_xor_b32_e32 v162, 0x8000, v162
	s_waitcnt lgkmcnt(9)
	v_mfma_f32_16x16x32_bf16 v[24:27], v[120:123], v[70:73], v[24:27]
	v_mfma_f32_16x16x32_bf16 v[20:23], v[120:123], v[74:77], v[20:23]
	v_mfma_f32_16x16x32_bf16 v[16:19], v[120:123], v[78:81], v[16:19]
	v_mfma_f32_16x16x32_bf16 v[12:15], v[120:123], v[82:85], v[12:15]
	v_xor_b32_e32 v161, 0x8000, v161
	v_xor_b32_e32 v163, 0x8000, v163
	s_waitcnt lgkmcnt(8)
	v_mfma_f32_16x16x32_bf16 v[8:11], v[124:127], v[70:73], v[8:11]
	v_mfma_f32_16x16x32_bf16 v[4:7], v[124:127], v[74:77], v[4:7]
	v_mfma_f32_16x16x32_bf16 v[48:51], v[124:127], v[78:81], v[48:51]
	v_mfma_f32_16x16x32_bf16 v[32:35], v[124:127], v[82:85], v[32:35]
	s_waitcnt lgkmcnt(3)
	v_mfma_f32_16x16x32_bf16 v[64:67], v[144:147], v[128:131], v[64:67]
	v_mfma_f32_16x16x32_bf16 v[60:63], v[144:147], v[132:135], v[60:63]
	v_mfma_f32_16x16x32_bf16 v[56:59], v[144:147], v[136:139], v[56:59]
	v_mfma_f32_16x16x32_bf16 v[52:55], v[144:147], v[140:143], v[52:55]
	s_waitcnt lgkmcnt(2)
	v_mfma_f32_16x16x32_bf16 v[44:47], v[148:151], v[128:131], v[44:47]
	v_mfma_f32_16x16x32_bf16 v[40:43], v[148:151], v[132:135], v[40:43]
	v_mfma_f32_16x16x32_bf16 v[36:39], v[148:151], v[136:139], v[36:39]
	v_mfma_f32_16x16x32_bf16 v[28:31], v[148:151], v[140:143], v[28:31]
	s_cmpk_eq_i32 s52, 0x780
	s_waitcnt lgkmcnt(1)
	v_mfma_f32_16x16x32_bf16 v[24:27], v[152:155], v[128:131], v[24:27]
	v_mfma_f32_16x16x32_bf16 v[20:23], v[152:155], v[132:135], v[20:23]
	v_mfma_f32_16x16x32_bf16 v[16:19], v[152:155], v[136:139], v[16:19]
	v_mfma_f32_16x16x32_bf16 v[12:15], v[152:155], v[140:143], v[12:15]
	s_waitcnt lgkmcnt(0)
	s_waitcnt vmcnt(0)
	s_barrier
	v_mfma_f32_16x16x32_bf16 v[8:11], v[156:159], v[128:131], v[8:11]
	v_mfma_f32_16x16x32_bf16 v[4:7], v[156:159], v[132:135], v[4:7]
	v_mfma_f32_16x16x32_bf16 v[48:51], v[156:159], v[136:139], v[48:51]
	v_mfma_f32_16x16x32_bf16 v[32:35], v[156:159], v[140:143], v[32:35]
	s_cbranch_scc0 .LBB0_627
	s_mov_b32 s37, 0x8000
	v_lshl_add_u32 v69, v69, 1, s37
	v_add_u32_e32 v90, v69, v68
	ds_read_b128 v[70:73], v90 offset:16384
	v_add_u32_e32 v69, v69, v3
	ds_read_b128 v[74:77], v69
	ds_read_b128 v[78:81], v69 offset:2048
	ds_read_b128 v[82:85], v69 offset:4096
	ds_read_b128 v[86:89], v69 offset:6144
	v_lshl_add_u32 v1, v1, 1, s37
	v_add_u32_e32 v98, v1, v68
	ds_read_b128 v[94:97], v98 offset:20480
	s_waitcnt lgkmcnt(4)
	v_mfma_f32_16x16x32_bf16 v[64:67], v[70:73], v[74:77], v[64:67]
	v_add_u32_e32 v1, v1, v3
	s_and_b64 vcc, exec, s[46:47]
	s_waitcnt lgkmcnt(3)
	v_mfma_f32_16x16x32_bf16 v[60:63], v[70:73], v[78:81], v[60:63]
	s_waitcnt lgkmcnt(2)
	v_mfma_f32_16x16x32_bf16 v[56:59], v[70:73], v[82:85], v[56:59]
	s_waitcnt lgkmcnt(1)
	v_mfma_f32_16x16x32_bf16 v[52:55], v[70:73], v[86:89], v[52:55]
	ds_read_b128 v[70:73], v90 offset:18432
	s_waitcnt lgkmcnt(0)
	v_mfma_f32_16x16x32_bf16 v[44:47], v[70:73], v[74:77], v[44:47]
	v_mfma_f32_16x16x32_bf16 v[40:43], v[70:73], v[78:81], v[40:43]
	v_mfma_f32_16x16x32_bf16 v[36:39], v[70:73], v[82:85], v[36:39]
	v_mfma_f32_16x16x32_bf16 v[28:31], v[70:73], v[86:89], v[28:31]
	ds_read_b128 v[70:73], v90 offset:20480
	s_waitcnt lgkmcnt(0)
	v_mfma_f32_16x16x32_bf16 v[24:27], v[70:73], v[74:77], v[24:27]
	v_mfma_f32_16x16x32_bf16 v[20:23], v[70:73], v[78:81], v[20:23]
	v_mfma_f32_16x16x32_bf16 v[16:19], v[70:73], v[82:85], v[16:19]
	v_mfma_f32_16x16x32_bf16 v[12:15], v[70:73], v[86:89], v[12:15]
	ds_read_b128 v[70:73], v90 offset:22528
	ds_read_b128 v[90:93], v1 offset:6144
	s_waitcnt lgkmcnt(1)
	v_mfma_f32_16x16x32_bf16 v[8:11], v[70:73], v[74:77], v[8:11]
	v_mfma_f32_16x16x32_bf16 v[4:7], v[70:73], v[78:81], v[4:7]
	ds_read_b128 v[78:81], v1
	v_mfma_f32_16x16x32_bf16 v[74:77], v[70:73], v[82:85], v[48:51]
	ds_read_b128 v[82:85], v1 offset:2048
	s_nop 1
	ds_read_b128 v[48:51], v98 offset:16384
	v_mfma_f32_16x16x32_bf16 v[68:71], v[70:73], v[86:89], v[32:35]
	ds_read_b128 v[86:89], v1 offset:4096
	s_nop 1
	ds_read_b128 v[32:35], v98 offset:18432
	s_waitcnt lgkmcnt(2)
	v_mfma_f32_16x16x32_bf16 v[64:67], v[48:51], v[78:81], v[64:67]
	v_mfma_f32_16x16x32_bf16 v[60:63], v[48:51], v[82:85], v[60:63]
	s_waitcnt lgkmcnt(1)
	v_mfma_f32_16x16x32_bf16 v[56:59], v[48:51], v[86:89], v[56:59]
	v_mfma_f32_16x16x32_bf16 v[52:55], v[48:51], v[90:93], v[52:55]
	s_waitcnt lgkmcnt(0)
	v_mfma_f32_16x16x32_bf16 v[48:51], v[32:35], v[78:81], v[44:47]
	v_mfma_f32_16x16x32_bf16 v[44:47], v[32:35], v[82:85], v[40:43]
	v_mfma_f32_16x16x32_bf16 v[40:43], v[32:35], v[86:89], v[36:39]
	v_mfma_f32_16x16x32_bf16 v[36:39], v[32:35], v[90:93], v[28:31]
	v_mfma_f32_16x16x32_bf16 v[32:35], v[94:97], v[78:81], v[24:27]
	v_mfma_f32_16x16x32_bf16 v[28:31], v[94:97], v[82:85], v[20:23]
	v_mfma_f32_16x16x32_bf16 v[24:27], v[94:97], v[86:89], v[16:19]
	v_mfma_f32_16x16x32_bf16 v[20:23], v[94:97], v[90:93], v[12:15]
	ds_read_b128 v[94:97], v98 offset:22528
	s_waitcnt vmcnt(0)
	s_waitcnt lgkmcnt(0)
	v_mfma_f32_16x16x32_bf16 v[16:19], v[94:97], v[78:81], v[8:11]
	s_barrier
	v_mfma_f32_16x16x32_bf16 v[12:15], v[94:97], v[82:85], v[4:7]
	v_mfma_f32_16x16x32_bf16 v[8:11], v[94:97], v[86:89], v[74:77]
	v_mfma_f32_16x16x32_bf16 v[4:7], v[94:97], v[90:93], v[68:71]
	s_cbranch_vccz .LBB0_630
	s_ashr_i32 s41, s40, 31
	v_mov_b32_e32 v1, v168
	s_lshl_b64 s[20:21], s[40:41], 18
	v_readlane_b32 s2, v252, 32
	v_readlane_b32 s3, v252, 33
	v_ashrrev_i32_e32 v68, 3, v1
	s_add_u32 s20, s2, s20
	v_xor_b32_e32 v3, v68, v1
	v_ashrrev_i32_e32 v69, 31, v68
	s_addc_u32 s21, s3, s21
	v_lshlrev_b64 v[68:69], 11, v[68:69]
	v_lshlrev_b32_e32 v3, 4, v3
	v_lshlrev_b32_e32 v1, 4, v1
	s_ashr_i32 s43, s42, 31
	v_lshl_add_u64 v[70:71], s[20:21], 0, v[68:69]
	v_and_b32_e32 v72, 0x70, v3
	v_mov_b32_e32 v73, v2
	v_readfirstlane_b32 s2, v1
	v_add_u32_e32 v3, 0x1000, v1
	s_lshl_b64 s[46:47], s[42:43], 18
	v_readlane_b32 s1, v252, 19
	v_lshl_add_u64 v[70:71], v[70:71], 0, v[72:73]
	s_mov_b32 m0, s2
	v_readfirstlane_b32 s2, v3
	v_add_u32_e32 v3, 0x2000, v1
	s_add_u32 s46, s1, s46
	v_readlane_b32 s1, v252, 20
	global_load_lds_dwordx4 v[70:71], off
	v_lshl_add_u64 v[74:75], v[70:71], 0, s[24:25]
	s_mov_b32 m0, s2
	v_readfirstlane_b32 s2, v3
	v_add_u32_e32 v3, 0x3000, v1
	s_addc_u32 s47, s1, s47
	global_load_lds_dwordx4 v[74:75], off
	v_lshl_add_u64 v[74:75], v[70:71], 0, s[26:27]
	s_mov_b32 m0, s2
	v_readfirstlane_b32 s2, v3
	v_add_u32_e32 v3, 0x4000, v1
	v_lshl_add_u64 v[68:69], s[46:47], 0, v[68:69]
	global_load_lds_dwordx4 v[74:75], off
	v_lshl_add_u64 v[70:71], v[70:71], 0, s[28:29]
	s_mov_b32 m0, s2
	v_readfirstlane_b32 s2, v3
	v_add_u32_e32 v3, 0x5000, v1
	global_load_lds_dwordx4 v[70:71], off
	v_lshl_add_u64 v[68:69], v[68:69], 0, v[72:73]
	s_mov_b32 m0, s2
	v_readfirstlane_b32 s2, v3
	v_add_u32_e32 v3, 0x6000, v1
	global_load_lds_dwordx4 v[68:69], off
	v_lshl_add_u64 v[70:71], v[68:69], 0, s[24:25]
	s_mov_b32 m0, s2
	v_readfirstlane_b32 s2, v3
	v_add_u32_e32 v1, 0x7000, v1
	global_load_lds_dwordx4 v[70:71], off
	v_lshl_add_u64 v[70:71], v[68:69], 0, s[26:27]
	s_mov_b32 m0, s2
	v_readfirstlane_b32 s2, v1
	global_load_lds_dwordx4 v[70:71], off
	v_lshl_add_u64 v[68:69], v[68:69], 0, s[28:29]
	s_mov_b32 m0, s2
	s_nop 0
	global_load_lds_dwordx4 v[68:69], off
